# GEMM K-loops: the no-op s_setprio 0 / s_setprio 1 pairs in the middle of each MFMA block removed
# speedup vs baseline: 1.0022x; 1.0022x over previous
.LBB0_120:
	ds_read_b128 v[154:157], v150
	ds_read_b128 v[158:161], v150 offset:1024
	ds_read_b128 v[162:165], v150 offset:2048
	ds_read_b128 v[166:169], v150 offset:3072
	ds_read_b128 v[170:173], v151
	ds_read_b128 v[174:177], v151 offset:1024
	ds_read_b128 v[178:181], v151 offset:2048
	ds_read_b128 v[182:185], v151 offset:3072
	s_add_u32 s46, s44, 0xfff80080
	s_addc_u32 s47, s45, -1
	s_cmp_eq_u32 s73, 28
	s_cselect_b32 s49, s25, s47
	s_cselect_b32 s48, s69, s46
	s_cselect_b32 s47, s21, s72
	s_cselect_b32 s46, s70, s71
	v_lshl_add_u64 v[144:145], s[44:45], 0, v[138:139]
	s_add_i32 m0, s31, 0xc000
	ds_read_b128 v[186:189], v152
	ds_read_b128 v[190:193], v152 offset:1024
	ds_read_b128 v[194:197], v152 offset:2048
	ds_read_b128 v[198:201], v152 offset:3072
	ds_read_b128 v[202:205], v152 offset:4096
	ds_read_b128 v[206:209], v152 offset:5120
	ds_read_b128 v[210:213], v152 offset:6144
	ds_read_b128 v[214:217], v152 offset:7168
	global_load_lds_dwordx4 v[144:145], off
	v_lshl_add_u64 v[144:145], s[44:45], 0, v[136:137]
	s_add_i32 m0, s31, 0xe000
	s_nop 0
	global_load_lds_dwordx4 v[144:145], off
	s_waitcnt vmcnt(8)
	s_waitcnt lgkmcnt(0)
	s_barrier
	s_setprio 1
	s_waitcnt lgkmcnt(0)
	v_mfma_f32_16x16x32_bf16 v[124:127], v[154:157], v[186:189], v[124:127]
	v_mfma_f32_16x16x32_bf16 v[120:123], v[162:165], v[186:189], v[120:123]
	v_mfma_f32_16x16x32_bf16 v[116:119], v[154:157], v[194:197], v[116:119]
	v_mfma_f32_16x16x32_bf16 v[108:111], v[162:165], v[194:197], v[108:111]
	v_mfma_f32_16x16x32_bf16 v[100:103], v[154:157], v[202:205], v[100:103]
	v_mfma_f32_16x16x32_bf16 v[92:95], v[162:165], v[202:205], v[92:95]
	v_mfma_f32_16x16x32_bf16 v[84:87], v[154:157], v[210:213], v[84:87]
	v_mfma_f32_16x16x32_bf16 v[76:79], v[162:165], v[210:213], v[76:79]
	v_mfma_f32_16x16x32_bf16 v[124:127], v[158:161], v[190:193], v[124:127]
	v_mfma_f32_16x16x32_bf16 v[120:123], v[166:169], v[190:193], v[120:123]
	v_mfma_f32_16x16x32_bf16 v[116:119], v[158:161], v[198:201], v[116:119]
	v_mfma_f32_16x16x32_bf16 v[108:111], v[166:169], v[198:201], v[108:111]
	v_mfma_f32_16x16x32_bf16 v[100:103], v[158:161], v[206:209], v[100:103]
	v_mfma_f32_16x16x32_bf16 v[92:95], v[166:169], v[206:209], v[92:95]
	v_mfma_f32_16x16x32_bf16 v[84:87], v[158:161], v[214:217], v[84:87]
	v_mfma_f32_16x16x32_bf16 v[76:79], v[166:169], v[214:217], v[76:79]
	v_mfma_f32_16x16x32_bf16 v[112:115], v[170:173], v[186:189], v[112:115]
	v_mfma_f32_16x16x32_bf16 v[104:107], v[178:181], v[186:189], v[104:107]
	v_mfma_f32_16x16x32_bf16 v[96:99], v[170:173], v[194:197], v[96:99]
	v_mfma_f32_16x16x32_bf16 v[88:91], v[178:181], v[194:197], v[88:91]
	v_mfma_f32_16x16x32_bf16 v[80:83], v[170:173], v[202:205], v[80:83]
	v_mfma_f32_16x16x32_bf16 v[72:75], v[178:181], v[202:205], v[72:75]
	v_mfma_f32_16x16x32_bf16 v[68:71], v[170:173], v[210:213], v[68:71]
	v_mfma_f32_16x16x32_bf16 v[64:67], v[178:181], v[210:213], v[64:67]
	v_mfma_f32_16x16x32_bf16 v[112:115], v[174:177], v[190:193], v[112:115]
	v_mfma_f32_16x16x32_bf16 v[104:107], v[182:185], v[190:193], v[104:107]
	v_mfma_f32_16x16x32_bf16 v[96:99], v[174:177], v[198:201], v[96:99]
	v_mfma_f32_16x16x32_bf16 v[88:91], v[182:185], v[198:201], v[88:91]
	v_mfma_f32_16x16x32_bf16 v[80:83], v[174:177], v[206:209], v[80:83]
	v_mfma_f32_16x16x32_bf16 v[72:75], v[182:185], v[206:209], v[72:75]
	v_mfma_f32_16x16x32_bf16 v[68:71], v[174:177], v[214:217], v[68:71]
	v_mfma_f32_16x16x32_bf16 v[64:67], v[182:185], v[214:217], v[64:67]
	s_setprio 0
	s_barrier
	s_add_i32 s74, s62, s55
	v_lshl_add_u64 v[144:145], s[46:47], 0, v[130:131]
	s_mov_b32 m0, s74
	ds_read_b128 v[186:189], v152 offset:16384
	ds_read_b128 v[190:193], v152 offset:17408
	ds_read_b128 v[194:197], v152 offset:18432
	ds_read_b128 v[198:201], v152 offset:19456
	ds_read_b128 v[202:205], v152 offset:20480
	ds_read_b128 v[206:209], v152 offset:21504
	ds_read_b128 v[210:213], v152 offset:22528
	ds_read_b128 v[214:217], v152 offset:23552
	global_load_lds_dwordx4 v[144:145], off
	s_add_i32 m0, s74, 0x2000
	s_add_u32 s74, s46, 0x80000
	v_lshl_add_u64 v[218:219], s[46:47], 0, v[134:135]
	s_addc_u32 s75, s47, 0
	s_add_i32 s76, s63, s55
	global_load_lds_dwordx4 v[218:219], off
	v_lshl_add_u64 v[220:221], s[74:75], 0, v[130:131]
	s_mov_b32 m0, s76
	v_lshl_add_u64 v[222:223], s[48:49], 0, v[132:133]
	global_load_lds_dwordx4 v[220:221], off
	v_lshl_add_u64 v[220:221], s[74:75], 0, v[134:135]
	s_add_i32 m0, s76, 0x2000
	s_nop 0
	global_load_lds_dwordx4 v[220:221], off
	v_lshl_add_u64 v[220:221], s[48:49], 0, v[128:129]
	s_mov_b32 m0, s31
	s_nop 0
	global_load_lds_dwordx4 v[220:221], off
	s_mov_b32 m0, s56
	s_nop 0
	global_load_lds_dwordx4 v[222:223], off
	s_waitcnt vmcnt(8)
	s_waitcnt lgkmcnt(0)
	s_barrier
	s_setprio 1
	s_waitcnt lgkmcnt(0)
	v_mfma_f32_16x16x32_bf16 v[60:63], v[154:157], v[186:189], v[60:63]
	v_mfma_f32_16x16x32_bf16 v[56:59], v[162:165], v[186:189], v[56:59]
	v_mfma_f32_16x16x32_bf16 v[52:55], v[154:157], v[194:197], v[52:55]
	v_mfma_f32_16x16x32_bf16 v[44:47], v[162:165], v[194:197], v[44:47]
	v_mfma_f32_16x16x32_bf16 v[36:39], v[154:157], v[202:205], v[36:39]
	v_mfma_f32_16x16x32_bf16 v[28:31], v[162:165], v[202:205], v[28:31]
	v_mfma_f32_16x16x32_bf16 v[20:23], v[154:157], v[210:213], v[20:23]
	v_mfma_f32_16x16x32_bf16 v[12:15], v[162:165], v[210:213], v[12:15]
	v_mfma_f32_16x16x32_bf16 v[60:63], v[158:161], v[190:193], v[60:63]
	v_mfma_f32_16x16x32_bf16 v[56:59], v[166:169], v[190:193], v[56:59]
	v_mfma_f32_16x16x32_bf16 v[52:55], v[158:161], v[198:201], v[52:55]
	v_mfma_f32_16x16x32_bf16 v[44:47], v[166:169], v[198:201], v[44:47]
	v_mfma_f32_16x16x32_bf16 v[36:39], v[158:161], v[206:209], v[36:39]
	v_mfma_f32_16x16x32_bf16 v[28:31], v[166:169], v[206:209], v[28:31]
	v_mfma_f32_16x16x32_bf16 v[20:23], v[158:161], v[214:217], v[20:23]
	v_mfma_f32_16x16x32_bf16 v[12:15], v[166:169], v[214:217], v[12:15]
	v_mfma_f32_16x16x32_bf16 v[48:51], v[170:173], v[186:189], v[48:51]
	v_mfma_f32_16x16x32_bf16 v[40:43], v[178:181], v[186:189], v[40:43]
	v_mfma_f32_16x16x32_bf16 v[32:35], v[170:173], v[194:197], v[32:35]
	v_mfma_f32_16x16x32_bf16 v[24:27], v[178:181], v[194:197], v[24:27]
	v_mfma_f32_16x16x32_bf16 v[16:19], v[170:173], v[202:205], v[16:19]
	v_mfma_f32_16x16x32_bf16 v[8:11], v[178:181], v[202:205], v[8:11]
	v_mfma_f32_16x16x32_bf16 v[4:7], v[170:173], v[210:213], v[4:7]
	v_mfma_f32_16x16x32_bf16 v[0:3], v[178:181], v[210:213], v[0:3]
	v_mfma_f32_16x16x32_bf16 v[48:51], v[174:177], v[190:193], v[48:51]
	v_mfma_f32_16x16x32_bf16 v[40:43], v[182:185], v[190:193], v[40:43]
	v_mfma_f32_16x16x32_bf16 v[32:35], v[174:177], v[198:201], v[32:35]
	v_mfma_f32_16x16x32_bf16 v[24:27], v[182:185], v[198:201], v[24:27]
	v_mfma_f32_16x16x32_bf16 v[16:19], v[174:177], v[206:209], v[16:19]
	v_mfma_f32_16x16x32_bf16 v[8:11], v[182:185], v[206:209], v[8:11]
	v_mfma_f32_16x16x32_bf16 v[4:7], v[174:177], v[214:217], v[4:7]
	v_mfma_f32_16x16x32_bf16 v[0:3], v[182:185], v[214:217], v[0:3]
	s_setprio 0
	s_barrier
	s_add_i32 s74, 0, 0x18000
	v_add_u32_e32 v153, s74, v148
	s_add_i32 s75, 0, 0x1c000
	ds_read_b128 v[154:157], v153
	ds_read_b128 v[158:161], v153 offset:1024
	ds_read_b128 v[162:165], v153 offset:2048
	ds_read_b128 v[166:169], v153 offset:3072
	v_add_u32_e32 v153, s75, v148
	ds_read_b128 v[170:173], v153
	ds_read_b128 v[174:177], v153 offset:1024
	ds_read_b128 v[178:181], v153 offset:2048
	ds_read_b128 v[182:185], v153 offset:3072
	s_add_u32 s48, s48, 0x80000
	s_addc_u32 s49, s49, 0
	s_mov_b32 m0, s57
	v_lshl_add_u64 v[224:225], s[48:49], 0, v[128:129]
	ds_read_b128 v[186:189], v152 offset:32768
	ds_read_b128 v[190:193], v152 offset:33792
	ds_read_b128 v[194:197], v152 offset:34816
	ds_read_b128 v[198:201], v152 offset:35840
	ds_read_b128 v[202:205], v152 offset:36864
	ds_read_b128 v[206:209], v152 offset:37888
	ds_read_b128 v[210:213], v152 offset:38912
	ds_read_b128 v[214:217], v152 offset:39936
	global_load_lds_dwordx4 v[224:225], off
	v_lshl_add_u64 v[224:225], s[48:49], 0, v[132:133]
	s_mov_b32 m0, s58
	s_nop 0
	global_load_lds_dwordx4 v[224:225], off
	s_waitcnt vmcnt(8)
	s_waitcnt lgkmcnt(0)
	s_barrier
	s_setprio 1
	s_waitcnt lgkmcnt(0)
	v_mfma_f32_16x16x32_bf16 v[124:127], v[154:157], v[186:189], v[124:127]
	v_mfma_f32_16x16x32_bf16 v[120:123], v[162:165], v[186:189], v[120:123]
	v_mfma_f32_16x16x32_bf16 v[116:119], v[154:157], v[194:197], v[116:119]
	v_mfma_f32_16x16x32_bf16 v[108:111], v[162:165], v[194:197], v[108:111]
	v_mfma_f32_16x16x32_bf16 v[100:103], v[154:157], v[202:205], v[100:103]
	v_mfma_f32_16x16x32_bf16 v[92:95], v[162:165], v[202:205], v[92:95]
	v_mfma_f32_16x16x32_bf16 v[84:87], v[154:157], v[210:213], v[84:87]
	v_mfma_f32_16x16x32_bf16 v[76:79], v[162:165], v[210:213], v[76:79]
	v_mfma_f32_16x16x32_bf16 v[124:127], v[158:161], v[190:193], v[124:127]
	v_mfma_f32_16x16x32_bf16 v[120:123], v[166:169], v[190:193], v[120:123]
	v_mfma_f32_16x16x32_bf16 v[116:119], v[158:161], v[198:201], v[116:119]
	v_mfma_f32_16x16x32_bf16 v[108:111], v[166:169], v[198:201], v[108:111]
	v_mfma_f32_16x16x32_bf16 v[100:103], v[158:161], v[206:209], v[100:103]
	v_mfma_f32_16x16x32_bf16 v[92:95], v[166:169], v[206:209], v[92:95]
	v_mfma_f32_16x16x32_bf16 v[84:87], v[158:161], v[214:217], v[84:87]
	v_mfma_f32_16x16x32_bf16 v[76:79], v[166:169], v[214:217], v[76:79]
	v_mfma_f32_16x16x32_bf16 v[112:115], v[170:173], v[186:189], v[112:115]
	v_mfma_f32_16x16x32_bf16 v[104:107], v[178:181], v[186:189], v[104:107]
	v_mfma_f32_16x16x32_bf16 v[96:99], v[170:173], v[194:197], v[96:99]
	v_mfma_f32_16x16x32_bf16 v[88:91], v[178:181], v[194:197], v[88:91]
	v_mfma_f32_16x16x32_bf16 v[80:83], v[170:173], v[202:205], v[80:83]
	v_mfma_f32_16x16x32_bf16 v[72:75], v[178:181], v[202:205], v[72:75]
	v_mfma_f32_16x16x32_bf16 v[68:71], v[170:173], v[210:213], v[68:71]
	v_mfma_f32_16x16x32_bf16 v[64:67], v[178:181], v[210:213], v[64:67]
	v_mfma_f32_16x16x32_bf16 v[112:115], v[174:177], v[190:193], v[112:115]
	v_mfma_f32_16x16x32_bf16 v[104:107], v[182:185], v[190:193], v[104:107]
	v_mfma_f32_16x16x32_bf16 v[96:99], v[174:177], v[198:201], v[96:99]
	v_mfma_f32_16x16x32_bf16 v[88:91], v[182:185], v[198:201], v[88:91]
	v_mfma_f32_16x16x32_bf16 v[80:83], v[174:177], v[206:209], v[80:83]
	v_mfma_f32_16x16x32_bf16 v[72:75], v[182:185], v[206:209], v[72:75]
	v_mfma_f32_16x16x32_bf16 v[68:71], v[174:177], v[214:217], v[68:71]
	v_mfma_f32_16x16x32_bf16 v[64:67], v[182:185], v[214:217], v[64:67]
	s_setprio 0
	s_barrier
	s_add_i32 s48, s74, s55
	v_lshl_add_u64 v[144:145], v[144:145], 0, s[8:9]
	s_mov_b32 m0, s48
	ds_read_b128 v[186:189], v152 offset:49152
	ds_read_b128 v[190:193], v152 offset:50176
	ds_read_b128 v[194:197], v152 offset:51200
	ds_read_b128 v[198:201], v152 offset:52224
	ds_read_b128 v[202:205], v152 offset:53248
	ds_read_b128 v[206:209], v152 offset:54272
	ds_read_b128 v[210:213], v152 offset:55296
	ds_read_b128 v[214:217], v152 offset:56320
	global_load_lds_dwordx4 v[144:145], off
	s_add_i32 m0, s48, 0x2000
	s_add_u32 s46, s46, 0x80080
	v_lshl_add_u64 v[144:145], v[218:219], 0, s[8:9]
	s_addc_u32 s47, s47, 0
	s_add_i32 s48, s75, s55
	global_load_lds_dwordx4 v[144:145], off
	v_lshl_add_u64 v[144:145], s[46:47], 0, v[130:131]
	s_mov_b32 m0, s48
	s_nop 0
	global_load_lds_dwordx4 v[144:145], off
	v_lshl_add_u64 v[144:145], s[46:47], 0, v[134:135]
	s_add_i32 m0, s48, 0x2000
	s_nop 0
	global_load_lds_dwordx4 v[144:145], off
	v_lshl_add_u64 v[144:145], v[220:221], 0, s[8:9]
	s_mov_b32 m0, s60
	s_nop 0
	global_load_lds_dwordx4 v[144:145], off
	v_lshl_add_u64 v[144:145], v[222:223], 0, s[8:9]
	s_mov_b32 m0, s61
	s_nop 0
	global_load_lds_dwordx4 v[144:145], off
	s_waitcnt vmcnt(8)
	s_waitcnt lgkmcnt(0)
	s_barrier
	s_setprio 1
	s_waitcnt lgkmcnt(0)
	v_mfma_f32_16x16x32_bf16 v[60:63], v[154:157], v[186:189], v[60:63]
	v_mfma_f32_16x16x32_bf16 v[56:59], v[162:165], v[186:189], v[56:59]
	v_mfma_f32_16x16x32_bf16 v[52:55], v[154:157], v[194:197], v[52:55]
	v_mfma_f32_16x16x32_bf16 v[44:47], v[162:165], v[194:197], v[44:47]
	v_mfma_f32_16x16x32_bf16 v[36:39], v[154:157], v[202:205], v[36:39]
	v_mfma_f32_16x16x32_bf16 v[28:31], v[162:165], v[202:205], v[28:31]
	v_mfma_f32_16x16x32_bf16 v[20:23], v[154:157], v[210:213], v[20:23]
	v_mfma_f32_16x16x32_bf16 v[12:15], v[162:165], v[210:213], v[12:15]
	v_mfma_f32_16x16x32_bf16 v[60:63], v[158:161], v[190:193], v[60:63]
	v_mfma_f32_16x16x32_bf16 v[56:59], v[166:169], v[190:193], v[56:59]
	v_mfma_f32_16x16x32_bf16 v[52:55], v[158:161], v[198:201], v[52:55]
	v_mfma_f32_16x16x32_bf16 v[44:47], v[166:169], v[198:201], v[44:47]
	v_mfma_f32_16x16x32_bf16 v[36:39], v[158:161], v[206:209], v[36:39]
	v_mfma_f32_16x16x32_bf16 v[28:31], v[166:169], v[206:209], v[28:31]
	v_mfma_f32_16x16x32_bf16 v[20:23], v[158:161], v[214:217], v[20:23]
	v_mfma_f32_16x16x32_bf16 v[12:15], v[166:169], v[214:217], v[12:15]
	v_mfma_f32_16x16x32_bf16 v[48:51], v[170:173], v[186:189], v[48:51]
	v_mfma_f32_16x16x32_bf16 v[40:43], v[178:181], v[186:189], v[40:43]
	v_mfma_f32_16x16x32_bf16 v[32:35], v[170:173], v[194:197], v[32:35]
	v_mfma_f32_16x16x32_bf16 v[24:27], v[178:181], v[194:197], v[24:27]
	v_mfma_f32_16x16x32_bf16 v[16:19], v[170:173], v[202:205], v[16:19]
	v_mfma_f32_16x16x32_bf16 v[8:11], v[178:181], v[202:205], v[8:11]
	v_mfma_f32_16x16x32_bf16 v[4:7], v[170:173], v[210:213], v[4:7]
	v_mfma_f32_16x16x32_bf16 v[0:3], v[178:181], v[210:213], v[0:3]
	v_mfma_f32_16x16x32_bf16 v[48:51], v[174:177], v[190:193], v[48:51]
	v_mfma_f32_16x16x32_bf16 v[40:43], v[182:185], v[190:193], v[40:43]
	v_mfma_f32_16x16x32_bf16 v[32:35], v[174:177], v[198:201], v[32:35]
	v_mfma_f32_16x16x32_bf16 v[24:27], v[182:185], v[198:201], v[24:27]
	v_mfma_f32_16x16x32_bf16 v[16:19], v[174:177], v[206:209], v[16:19]
	v_mfma_f32_16x16x32_bf16 v[8:11], v[182:185], v[206:209], v[8:11]
	v_mfma_f32_16x16x32_bf16 v[4:7], v[174:177], v[214:217], v[4:7]
	v_mfma_f32_16x16x32_bf16 v[0:3], v[182:185], v[214:217], v[0:3]
	s_setprio 0
	s_barrier
	s_add_i32 s73, s73, 2
	s_add_u32 s71, s71, 0x100
	s_addc_u32 s72, s72, 0
	s_add_u32 s44, s44, 0x100
	s_addc_u32 s45, s45, 0
	s_cmp_gt_u32 s73, 29
	s_cbranch_scc0 .LBB0_120
	s_and_b64 vcc, exec, s[10:11]
	v_readlane_b32 s69, v252, 20
	s_cbranch_vccz .LBB0_123
	s_barrier

.Lin_zskip:
	s_add_u32 s10, s8, 0xfff80080
	s_addc_u32 s11, s9, -1
	s_add_i32 s60, 0, 0x10000
	s_cmp_eq_u32 s59, 28
	s_cselect_b32 s15, s0, s11
	s_cselect_b32 s14, s1, s10
	v_add_u32_e32 v0, s60, v167
	s_cselect_b32 s11, s25, s58
	s_cselect_b32 s10, s27, s57
	s_add_i32 s62, 0, 0x14000
	ds_read_b128 v[130:133], v0
	ds_read_b128 v[158:161], v0 offset:1024
	ds_read_b128 v[162:165], v0 offset:2048
	ds_read_b128 v[170:173], v0 offset:3072
	v_add_u32_e32 v0, s62, v167
	ds_read_b128 v[174:177], v0
	ds_read_b128 v[178:181], v0 offset:1024
	ds_read_b128 v[182:185], v0 offset:2048
	ds_read_b128 v[186:189], v0 offset:3072
	s_mov_b32 m0, s52
	s_nop 0
	global_load_lds_dwordx4 v140, s[74:75]
	s_mov_b32 m0, s53
	s_nop 0
	global_load_lds_dwordx4 v136, s[74:75]
	s_add_i32 m0, s48, 0xc000
	ds_read_b128 v[190:193], v169
	ds_read_b128 v[194:197], v169 offset:1024
	ds_read_b128 v[198:201], v169 offset:2048
	ds_read_b128 v[216:219], v169 offset:3072
	ds_read_b128 v[220:223], v169 offset:4096
	ds_read_b128 v[224:227], v169 offset:5120
	ds_read_b128 v[228:231], v169 offset:6144
	ds_read_b128 v[232:235], v169 offset:7168
	global_load_lds_dwordx4 v156, s[8:9]
	s_add_i32 m0, s48, 0xe000
	s_nop 0
	global_load_lds_dwordx4 v146, s[8:9]
	s_waitcnt vmcnt(8)
	s_waitcnt lgkmcnt(0)
	s_barrier
	s_setprio 1
	s_waitcnt lgkmcnt(0)
	v_mfma_f32_16x16x32_bf16 v[126:129], v[130:133], v[190:193], 0
	s_add_i32 s101, s54, 1
	s_mul_i32 s76, s23, s101
	s_mul_hi_u32 s77, s22, s101
	v_mfma_f32_16x16x32_bf16 v[122:125], v[162:165], v[190:193], 0
	s_add_i32 s77, s77, s76
	s_mul_i32 s76, s22, s101
	s_add_u32 s76, s76, s2
	v_mfma_f32_16x16x32_bf16 v[110:113], v[130:133], v[198:201], 0
	s_addc_u32 s77, s77, s35
	v_cmp_lt_i64_e64 s[88:89], s[76:77], v[148:149]
	s_ashr_i32 s77, s76, 31
	v_mfma_f32_16x16x32_bf16 v[106:109], v[162:165], v[198:201], 0
	s_lshr_b32 s77, s77, 29
	s_add_i32 s77, s76, s77
	s_ashr_i32 s32, s77, 3
	v_mfma_f32_16x16x32_bf16 v[94:97], v[130:133], v[220:223], 0
	s_and_b32 s77, s77, -8
	s_sub_i32 s76, s76, s77
	s_cmp_lt_i32 s76, 0
	v_mfma_f32_16x16x32_bf16 v[90:93], v[162:165], v[220:223], 0
	s_cselect_b32 s77, s67, 0x1c0
	s_mul_i32 s76, s76, s77
	s_add_i32 s76, s76, s32
	v_mfma_f32_16x16x32_bf16 v[78:81], v[130:133], v[228:231], 0
	s_mul_hi_i32 s77, s76, 0x92492493
	s_add_i32 s77, s77, s76
	s_lshr_b32 s32, s77, 31
	v_mfma_f32_16x16x32_bf16 v[74:77], v[162:165], v[228:231], 0
	s_ashr_i32 s77, s77, 7
	s_add_i32 s77, s77, s32
	s_lshl_b32 s32, s77, 3
	v_mfma_f32_16x16x32_bf16 v[126:129], v[158:161], v[194:197], v[126:129]
	s_sub_i32 s34, 0x80, s32
	s_min_i32 s34, s34, 8
	s_abs_i32 s80, s34
	v_mfma_f32_16x16x32_bf16 v[122:125], v[170:173], v[194:197], v[122:125]
	v_cvt_f32_u32_e32 v157, s80
	s_sub_i32 s81, 0, s80
	s_mulk_i32 s77, 0xe0
	v_mfma_f32_16x16x32_bf16 v[110:113], v[158:161], v[216:219], v[110:113]
	s_sub_i32 s76, s76, s77
	v_rcp_iflag_f32_e32 v157, v157
	s_abs_i32 s77, s76
	v_mfma_f32_16x16x32_bf16 v[106:109], v[170:173], v[216:219], v[106:109]
	s_xor_b32 s100, s76, s34
	s_ashr_i32 s100, s100, 31
	v_mul_f32_e32 v157, 0x4f7ffffe, v157
	v_mfma_f32_16x16x32_bf16 v[94:97], v[158:161], v[224:227], v[94:97]
	v_cvt_u32_f32_e32 v157, v157
	s_nop 0
	v_readfirstlane_b32 s101, v157
	v_mfma_f32_16x16x32_bf16 v[90:93], v[170:173], v[224:227], v[90:93]
	s_mul_i32 s81, s81, s101
	s_mul_hi_u32 s81, s101, s81
	s_add_i32 s101, s101, s81
	v_mfma_f32_16x16x32_bf16 v[78:81], v[158:161], v[232:235], v[78:81]
	s_mul_hi_u32 s81, s77, s101
	s_mul_i32 s101, s81, s80
	s_sub_i32 s77, s77, s101
	v_mfma_f32_16x16x32_bf16 v[74:77], v[170:173], v[232:235], v[74:77]
	s_add_i32 vcc_lo, s81, 1
	s_sub_i32 s101, s77, s80
	s_cmp_ge_u32 s77, s80
	v_mfma_f32_16x16x32_bf16 v[118:121], v[174:177], v[190:193], 0
	s_cselect_b32 s81, vcc_lo, s81
	s_cselect_b32 s77, s101, s77
	s_add_i32 s101, s81, 1
	v_mfma_f32_16x16x32_bf16 v[114:117], v[182:185], v[190:193], 0
	s_cmp_ge_u32 s77, s80
	s_cselect_b32 s77, s101, s81
	s_xor_b32 s77, s77, s100
	v_mfma_f32_16x16x32_bf16 v[102:105], v[174:177], v[198:201], 0
	s_sub_i32 s80, s77, s100
	s_mul_i32 s77, s80, s34
	s_sub_i32 s76, s76, s77
	v_mfma_f32_16x16x32_bf16 v[98:101], v[182:185], v[198:201], 0
	s_add_i32 s81, s32, s76
	v_mfma_f32_16x16x32_bf16 v[86:89], v[174:177], v[220:223], 0
	v_mfma_f32_16x16x32_bf16 v[82:85], v[182:185], v[220:223], 0
	v_mfma_f32_16x16x32_bf16 v[70:73], v[174:177], v[228:231], 0
	v_mfma_f32_16x16x32_bf16 v[66:69], v[182:185], v[228:231], 0
	v_mfma_f32_16x16x32_bf16 v[118:121], v[178:181], v[194:197], v[118:121]
	v_mfma_f32_16x16x32_bf16 v[114:117], v[186:189], v[194:197], v[114:117]
	v_mfma_f32_16x16x32_bf16 v[102:105], v[178:181], v[216:219], v[102:105]
	v_mfma_f32_16x16x32_bf16 v[98:101], v[186:189], v[216:219], v[98:101]
	v_mfma_f32_16x16x32_bf16 v[86:89], v[178:181], v[224:227], v[86:89]
	v_mfma_f32_16x16x32_bf16 v[82:85], v[186:189], v[224:227], v[82:85]
	v_mfma_f32_16x16x32_bf16 v[70:73], v[178:181], v[232:235], v[70:73]
	v_mfma_f32_16x16x32_bf16 v[66:69], v[186:189], v[232:235], v[66:69]
	s_setprio 0
	s_barrier
	s_add_i32 s60, s60, s29
	s_add_u32 s72, s10, s44
	s_addc_u32 s73, s11, s45
	s_mov_b32 m0, s60
	ds_read_b128 v[190:193], v169 offset:16384
	ds_read_b128 v[194:197], v169 offset:17408
	ds_read_b128 v[198:201], v169 offset:18432
	ds_read_b128 v[216:219], v169 offset:19456
	ds_read_b128 v[220:223], v169 offset:20480
	ds_read_b128 v[224:227], v169 offset:21504
	ds_read_b128 v[228:231], v169 offset:22528
	ds_read_b128 v[232:235], v169 offset:23552
	global_load_lds_dwordx4 v138, s[10:11]
	s_add_i32 m0, s60, 0x2000
	s_add_u32 s60, s10, 0x80000
	s_addc_u32 s61, s11, 0
	s_add_i32 s62, s62, s29
	global_load_lds_dwordx4 v134, s[10:11]
	s_mov_b32 m0, s62
	s_add_u32 s74, s14, s44
	s_addc_u32 s75, s15, s45
	global_load_lds_dwordx4 v138, s[60:61]
	s_add_i32 m0, s62, 0x2000
	s_nop 0
	global_load_lds_dwordx4 v134, s[60:61]
	s_waitcnt vmcnt(6)
	s_waitcnt lgkmcnt(0)
	s_barrier
	s_setprio 1
	s_waitcnt lgkmcnt(0)
	v_mfma_f32_16x16x32_bf16 v[62:65], v[130:133], v[190:193], 0
	v_mfma_f32_16x16x32_bf16 v[58:61], v[162:165], v[190:193], 0
	v_mfma_f32_16x16x32_bf16 v[46:49], v[130:133], v[198:201], 0
	v_mfma_f32_16x16x32_bf16 v[42:45], v[162:165], v[198:201], 0
	v_mfma_f32_16x16x32_bf16 v[30:33], v[130:133], v[220:223], 0
	v_mfma_f32_16x16x32_bf16 v[26:29], v[162:165], v[220:223], 0
	v_mfma_f32_16x16x32_bf16 v[14:17], v[130:133], v[228:231], 0
	v_mfma_f32_16x16x32_bf16 v[10:13], v[162:165], v[228:231], 0
	v_mfma_f32_16x16x32_bf16 v[62:65], v[158:161], v[194:197], v[62:65]
	v_mfma_f32_16x16x32_bf16 v[58:61], v[170:173], v[194:197], v[58:61]
	v_mfma_f32_16x16x32_bf16 v[46:49], v[158:161], v[216:219], v[46:49]
	v_mfma_f32_16x16x32_bf16 v[42:45], v[170:173], v[216:219], v[42:45]
	v_mfma_f32_16x16x32_bf16 v[30:33], v[158:161], v[224:227], v[30:33]
	v_mfma_f32_16x16x32_bf16 v[26:29], v[170:173], v[224:227], v[26:29]
	v_mfma_f32_16x16x32_bf16 v[14:17], v[158:161], v[232:235], v[14:17]
	v_mfma_f32_16x16x32_bf16 v[10:13], v[170:173], v[232:235], v[10:13]
	v_mfma_f32_16x16x32_bf16 v[54:57], v[174:177], v[190:193], 0
	v_mfma_f32_16x16x32_bf16 v[50:53], v[182:185], v[190:193], 0
	v_mfma_f32_16x16x32_bf16 v[38:41], v[174:177], v[198:201], 0
	v_mfma_f32_16x16x32_bf16 v[34:37], v[182:185], v[198:201], 0
	v_mfma_f32_16x16x32_bf16 v[22:25], v[174:177], v[220:223], 0
	v_mfma_f32_16x16x32_bf16 v[18:21], v[182:185], v[220:223], 0
	v_mfma_f32_16x16x32_bf16 v[6:9], v[174:177], v[228:231], 0
	v_mfma_f32_16x16x32_bf16 v[2:5], v[182:185], v[228:231], 0
	v_mfma_f32_16x16x32_bf16 v[54:57], v[178:181], v[194:197], v[54:57]
	v_mfma_f32_16x16x32_bf16 v[50:53], v[186:189], v[194:197], v[50:53]
	v_mfma_f32_16x16x32_bf16 v[38:41], v[178:181], v[216:219], v[38:41]
	v_mfma_f32_16x16x32_bf16 v[34:37], v[186:189], v[216:219], v[34:37]
	v_mfma_f32_16x16x32_bf16 v[22:25], v[178:181], v[224:227], v[22:25]
	v_mfma_f32_16x16x32_bf16 v[18:21], v[186:189], v[224:227], v[18:21]
	v_mfma_f32_16x16x32_bf16 v[6:9], v[178:181], v[232:235], v[6:9]
	v_mfma_f32_16x16x32_bf16 v[2:5], v[186:189], v[232:235], v[2:5]
	s_setprio 0
	s_barrier
	s_add_i32 s60, 0, 0x18000
	v_add_u32_e32 v0, s60, v167
	s_add_i32 s61, 0, 0x1c000
	ds_read_b128 v[130:133], v0
	ds_read_b128 v[158:161], v0 offset:1024
	ds_read_b128 v[162:165], v0 offset:2048
	ds_read_b128 v[170:173], v0 offset:3072
	v_add_u32_e32 v0, s61, v167
	ds_read_b128 v[174:177], v0
	ds_read_b128 v[178:181], v0 offset:1024
	ds_read_b128 v[182:185], v0 offset:2048
	ds_read_b128 v[186:189], v0 offset:3072
	s_mov_b32 m0, s48
	s_nop 0
	global_load_lds_dwordx4 v140, s[14:15]
	s_mov_b32 m0, s49
	s_nop 0
	global_load_lds_dwordx4 v136, s[14:15]
	s_add_u32 s14, s14, 0x80000
	s_addc_u32 s15, s15, 0
	s_mov_b32 m0, s50
	ds_read_b128 v[190:193], v169 offset:32768
	ds_read_b128 v[194:197], v169 offset:33792
	ds_read_b128 v[198:201], v169 offset:34816
	ds_read_b128 v[216:219], v169 offset:35840
	ds_read_b128 v[220:223], v169 offset:36864
	ds_read_b128 v[224:227], v169 offset:37888
	ds_read_b128 v[228:231], v169 offset:38912
	ds_read_b128 v[232:235], v169 offset:39936
	global_load_lds_dwordx4 v140, s[14:15]
	s_mov_b32 m0, s51
	s_nop 0
	global_load_lds_dwordx4 v136, s[14:15]
	s_waitcnt vmcnt(8)
	s_waitcnt lgkmcnt(0)
	s_barrier
	s_setprio 1
	s_waitcnt lgkmcnt(0)
	v_mfma_f32_16x16x32_bf16 v[126:129], v[130:133], v[190:193], v[126:129]
	v_mfma_f32_16x16x32_bf16 v[122:125], v[162:165], v[190:193], v[122:125]
	v_mfma_f32_16x16x32_bf16 v[110:113], v[130:133], v[198:201], v[110:113]
	v_mfma_f32_16x16x32_bf16 v[106:109], v[162:165], v[198:201], v[106:109]
	v_mfma_f32_16x16x32_bf16 v[94:97], v[130:133], v[220:223], v[94:97]
	v_mfma_f32_16x16x32_bf16 v[90:93], v[162:165], v[220:223], v[90:93]
	v_mfma_f32_16x16x32_bf16 v[78:81], v[130:133], v[228:231], v[78:81]
	v_mfma_f32_16x16x32_bf16 v[74:77], v[162:165], v[228:231], v[74:77]
	v_mfma_f32_16x16x32_bf16 v[126:129], v[158:161], v[194:197], v[126:129]
	v_mfma_f32_16x16x32_bf16 v[122:125], v[170:173], v[194:197], v[122:125]
	v_mfma_f32_16x16x32_bf16 v[110:113], v[158:161], v[216:219], v[110:113]
	v_mfma_f32_16x16x32_bf16 v[106:109], v[170:173], v[216:219], v[106:109]
	v_mfma_f32_16x16x32_bf16 v[94:97], v[158:161], v[224:227], v[94:97]
	v_mfma_f32_16x16x32_bf16 v[90:93], v[170:173], v[224:227], v[90:93]
	v_mfma_f32_16x16x32_bf16 v[78:81], v[158:161], v[232:235], v[78:81]
	v_mfma_f32_16x16x32_bf16 v[74:77], v[170:173], v[232:235], v[74:77]
	v_mfma_f32_16x16x32_bf16 v[118:121], v[174:177], v[190:193], v[118:121]
	v_mfma_f32_16x16x32_bf16 v[114:117], v[182:185], v[190:193], v[114:117]
	v_mfma_f32_16x16x32_bf16 v[102:105], v[174:177], v[198:201], v[102:105]
	v_mfma_f32_16x16x32_bf16 v[98:101], v[182:185], v[198:201], v[98:101]
	v_mfma_f32_16x16x32_bf16 v[86:89], v[174:177], v[220:223], v[86:89]
	v_mfma_f32_16x16x32_bf16 v[82:85], v[182:185], v[220:223], v[82:85]
	v_mfma_f32_16x16x32_bf16 v[70:73], v[174:177], v[228:231], v[70:73]
	v_mfma_f32_16x16x32_bf16 v[66:69], v[182:185], v[228:231], v[66:69]
	v_mfma_f32_16x16x32_bf16 v[118:121], v[178:181], v[194:197], v[118:121]
	v_mfma_f32_16x16x32_bf16 v[114:117], v[186:189], v[194:197], v[114:117]
	v_mfma_f32_16x16x32_bf16 v[102:105], v[178:181], v[216:219], v[102:105]
	v_mfma_f32_16x16x32_bf16 v[98:101], v[186:189], v[216:219], v[98:101]
	v_mfma_f32_16x16x32_bf16 v[86:89], v[178:181], v[224:227], v[86:89]
	v_mfma_f32_16x16x32_bf16 v[82:85], v[186:189], v[224:227], v[82:85]
	v_mfma_f32_16x16x32_bf16 v[70:73], v[178:181], v[232:235], v[70:73]
	v_mfma_f32_16x16x32_bf16 v[66:69], v[186:189], v[232:235], v[66:69]
	s_setprio 0
	s_barrier
	s_add_i32 s14, s60, s29
	s_mov_b32 m0, s14
	ds_read_b128 v[190:193], v169 offset:49152
	ds_read_b128 v[194:197], v169 offset:50176
	ds_read_b128 v[198:201], v169 offset:51200
	ds_read_b128 v[216:219], v169 offset:52224
	ds_read_b128 v[220:223], v169 offset:53248
	ds_read_b128 v[224:227], v169 offset:54272
	ds_read_b128 v[228:231], v169 offset:55296
	ds_read_b128 v[232:235], v169 offset:56320
	global_load_lds_dwordx4 v138, s[72:73]
	s_add_i32 m0, s14, 0x2000
	s_add_u32 s10, s10, 0x80080
	s_addc_u32 s11, s11, 0
	s_add_i32 s14, s61, s29
	global_load_lds_dwordx4 v134, s[72:73]
	s_mov_b32 m0, s14
	s_nop 0
	global_load_lds_dwordx4 v138, s[10:11]
	s_add_i32 m0, s14, 0x2000
	s_nop 0
	global_load_lds_dwordx4 v134, s[10:11]
	s_waitcnt vmcnt(6)
	s_waitcnt lgkmcnt(0)
	s_barrier
	s_setprio 1
	s_waitcnt lgkmcnt(0)
	v_mfma_f32_16x16x32_bf16 v[62:65], v[130:133], v[190:193], v[62:65]
	s_add_i32 s59, s59, 2
	v_mfma_f32_16x16x32_bf16 v[58:61], v[162:165], v[190:193], v[58:61]
	s_add_u32 s57, s57, 0x100
	v_mfma_f32_16x16x32_bf16 v[46:49], v[130:133], v[198:201], v[46:49]
	s_addc_u32 s58, s58, 0
	v_mfma_f32_16x16x32_bf16 v[42:45], v[162:165], v[198:201], v[42:45]
	s_add_u32 s8, s8, 0x100
	v_mfma_f32_16x16x32_bf16 v[30:33], v[130:133], v[220:223], v[30:33]
	s_addc_u32 s9, s9, 0
	v_mfma_f32_16x16x32_bf16 v[26:29], v[162:165], v[220:223], v[26:29]
	s_add_u32 s10, s8, 0xfff80080
	v_mfma_f32_16x16x32_bf16 v[14:17], v[130:133], v[228:231], v[14:17]
	s_addc_u32 s11, s9, -1
	v_mfma_f32_16x16x32_bf16 v[10:13], v[162:165], v[228:231], v[10:13]
	s_add_i32 s60, 0, 0x10000
	v_mfma_f32_16x16x32_bf16 v[62:65], v[158:161], v[194:197], v[62:65]
	s_cmp_eq_u32 s59, 28
	v_mfma_f32_16x16x32_bf16 v[58:61], v[170:173], v[194:197], v[58:61]
	s_cselect_b32 s15, s0, s11
	v_mfma_f32_16x16x32_bf16 v[46:49], v[158:161], v[216:219], v[46:49]
	s_cselect_b32 s14, s1, s10
	v_mfma_f32_16x16x32_bf16 v[42:45], v[170:173], v[216:219], v[42:45]
	v_add_u32_e32 v0, s60, v167
	v_mfma_f32_16x16x32_bf16 v[30:33], v[158:161], v[224:227], v[30:33]
	s_cselect_b32 s11, s25, s58
	v_mfma_f32_16x16x32_bf16 v[26:29], v[170:173], v[224:227], v[26:29]
	s_cselect_b32 s10, s27, s57
	v_mfma_f32_16x16x32_bf16 v[14:17], v[158:161], v[232:235], v[14:17]
	s_add_i32 s62, 0, 0x14000
	v_mfma_f32_16x16x32_bf16 v[10:13], v[170:173], v[232:235], v[10:13]
	v_mfma_f32_16x16x32_bf16 v[54:57], v[174:177], v[190:193], v[54:57]
	v_mfma_f32_16x16x32_bf16 v[50:53], v[182:185], v[190:193], v[50:53]
	v_mfma_f32_16x16x32_bf16 v[38:41], v[174:177], v[198:201], v[38:41]
	v_mfma_f32_16x16x32_bf16 v[34:37], v[182:185], v[198:201], v[34:37]
	v_mfma_f32_16x16x32_bf16 v[22:25], v[174:177], v[220:223], v[22:25]
	v_mfma_f32_16x16x32_bf16 v[18:21], v[182:185], v[220:223], v[18:21]
	v_mfma_f32_16x16x32_bf16 v[6:9], v[174:177], v[228:231], v[6:9]
	v_mfma_f32_16x16x32_bf16 v[2:5], v[182:185], v[228:231], v[2:5]
	v_mfma_f32_16x16x32_bf16 v[54:57], v[178:181], v[194:197], v[54:57]
	v_mfma_f32_16x16x32_bf16 v[50:53], v[186:189], v[194:197], v[50:53]
	v_mfma_f32_16x16x32_bf16 v[38:41], v[178:181], v[216:219], v[38:41]
	v_mfma_f32_16x16x32_bf16 v[34:37], v[186:189], v[216:219], v[34:37]
	v_mfma_f32_16x16x32_bf16 v[22:25], v[178:181], v[224:227], v[22:25]
	v_mfma_f32_16x16x32_bf16 v[18:21], v[186:189], v[224:227], v[18:21]
	v_mfma_f32_16x16x32_bf16 v[6:9], v[178:181], v[232:235], v[6:9]
	v_mfma_f32_16x16x32_bf16 v[2:5], v[186:189], v[232:235], v[2:5]
	s_setprio 0
	s_barrier
	s_cmp_gt_u32 s59, 29
.LBB0_140:
	ds_read_b128 v[130:133], v0
	ds_read_b128 v[158:161], v0 offset:1024
	ds_read_b128 v[162:165], v0 offset:2048
	ds_read_b128 v[170:173], v0 offset:3072
	v_add_u32_e32 v0, s62, v167
	ds_read_b128 v[174:177], v0
	ds_read_b128 v[178:181], v0 offset:1024
	ds_read_b128 v[182:185], v0 offset:2048
	ds_read_b128 v[186:189], v0 offset:3072
	s_mov_b32 m0, s52
	s_nop 0
	global_load_lds_dwordx4 v140, s[74:75]
	s_mov_b32 m0, s53
	s_nop 0
	global_load_lds_dwordx4 v136, s[74:75]
	s_add_i32 m0, s48, 0xc000
	ds_read_b128 v[190:193], v169
	ds_read_b128 v[194:197], v169 offset:1024
	ds_read_b128 v[198:201], v169 offset:2048
	ds_read_b128 v[216:219], v169 offset:3072
	ds_read_b128 v[220:223], v169 offset:4096
	ds_read_b128 v[224:227], v169 offset:5120
	ds_read_b128 v[228:231], v169 offset:6144
	ds_read_b128 v[232:235], v169 offset:7168
	global_load_lds_dwordx4 v156, s[8:9]
	s_add_i32 m0, s48, 0xe000
	s_nop 0
	global_load_lds_dwordx4 v146, s[8:9]
	s_waitcnt vmcnt(8)
	s_waitcnt lgkmcnt(0)
	s_barrier
	s_setprio 1
	s_waitcnt lgkmcnt(0)
	v_mfma_f32_16x16x32_bf16 v[126:129], v[130:133], v[190:193], v[126:129]
	v_mfma_f32_16x16x32_bf16 v[122:125], v[162:165], v[190:193], v[122:125]
	v_mfma_f32_16x16x32_bf16 v[110:113], v[130:133], v[198:201], v[110:113]
	v_mfma_f32_16x16x32_bf16 v[106:109], v[162:165], v[198:201], v[106:109]
	v_mfma_f32_16x16x32_bf16 v[94:97], v[130:133], v[220:223], v[94:97]
	v_mfma_f32_16x16x32_bf16 v[90:93], v[162:165], v[220:223], v[90:93]
	v_mfma_f32_16x16x32_bf16 v[78:81], v[130:133], v[228:231], v[78:81]
	v_mfma_f32_16x16x32_bf16 v[74:77], v[162:165], v[228:231], v[74:77]
	v_mfma_f32_16x16x32_bf16 v[126:129], v[158:161], v[194:197], v[126:129]
	v_mfma_f32_16x16x32_bf16 v[122:125], v[170:173], v[194:197], v[122:125]
	v_mfma_f32_16x16x32_bf16 v[110:113], v[158:161], v[216:219], v[110:113]
	v_mfma_f32_16x16x32_bf16 v[106:109], v[170:173], v[216:219], v[106:109]
	v_mfma_f32_16x16x32_bf16 v[94:97], v[158:161], v[224:227], v[94:97]
	v_mfma_f32_16x16x32_bf16 v[90:93], v[170:173], v[224:227], v[90:93]
	v_mfma_f32_16x16x32_bf16 v[78:81], v[158:161], v[232:235], v[78:81]
	v_mfma_f32_16x16x32_bf16 v[74:77], v[170:173], v[232:235], v[74:77]
	v_mfma_f32_16x16x32_bf16 v[118:121], v[174:177], v[190:193], v[118:121]
	v_mfma_f32_16x16x32_bf16 v[114:117], v[182:185], v[190:193], v[114:117]
	v_mfma_f32_16x16x32_bf16 v[102:105], v[174:177], v[198:201], v[102:105]
	v_mfma_f32_16x16x32_bf16 v[98:101], v[182:185], v[198:201], v[98:101]
	v_mfma_f32_16x16x32_bf16 v[86:89], v[174:177], v[220:223], v[86:89]
	v_mfma_f32_16x16x32_bf16 v[82:85], v[182:185], v[220:223], v[82:85]
	v_mfma_f32_16x16x32_bf16 v[70:73], v[174:177], v[228:231], v[70:73]
	v_mfma_f32_16x16x32_bf16 v[66:69], v[182:185], v[228:231], v[66:69]
	v_mfma_f32_16x16x32_bf16 v[118:121], v[178:181], v[194:197], v[118:121]
	v_mfma_f32_16x16x32_bf16 v[114:117], v[186:189], v[194:197], v[114:117]
	v_mfma_f32_16x16x32_bf16 v[102:105], v[178:181], v[216:219], v[102:105]
	v_mfma_f32_16x16x32_bf16 v[98:101], v[186:189], v[216:219], v[98:101]
	v_mfma_f32_16x16x32_bf16 v[86:89], v[178:181], v[224:227], v[86:89]
	v_mfma_f32_16x16x32_bf16 v[82:85], v[186:189], v[224:227], v[82:85]
	v_mfma_f32_16x16x32_bf16 v[70:73], v[178:181], v[232:235], v[70:73]
	v_mfma_f32_16x16x32_bf16 v[66:69], v[186:189], v[232:235], v[66:69]
	s_setprio 0
	s_barrier
	s_add_i32 s60, s60, s29
	s_add_u32 s72, s10, s44
	s_addc_u32 s73, s11, s45
	s_mov_b32 m0, s60
	ds_read_b128 v[190:193], v169 offset:16384
	ds_read_b128 v[194:197], v169 offset:17408
	ds_read_b128 v[198:201], v169 offset:18432
	ds_read_b128 v[216:219], v169 offset:19456
	ds_read_b128 v[220:223], v169 offset:20480
	ds_read_b128 v[224:227], v169 offset:21504
	ds_read_b128 v[228:231], v169 offset:22528
	ds_read_b128 v[232:235], v169 offset:23552
	global_load_lds_dwordx4 v138, s[10:11]
	s_add_i32 m0, s60, 0x2000
	s_add_u32 s60, s10, 0x80000
	s_addc_u32 s61, s11, 0
	s_add_i32 s62, s62, s29
	global_load_lds_dwordx4 v134, s[10:11]
	s_mov_b32 m0, s62
	s_add_u32 s74, s14, s44
	s_addc_u32 s75, s15, s45
	global_load_lds_dwordx4 v138, s[60:61]
	s_add_i32 m0, s62, 0x2000
	s_nop 0
	global_load_lds_dwordx4 v134, s[60:61]
	s_waitcnt vmcnt(6)
	s_waitcnt lgkmcnt(0)
	s_barrier
	s_setprio 1
	s_waitcnt lgkmcnt(0)
	v_mfma_f32_16x16x32_bf16 v[62:65], v[130:133], v[190:193], v[62:65]
	v_mfma_f32_16x16x32_bf16 v[58:61], v[162:165], v[190:193], v[58:61]
	v_mfma_f32_16x16x32_bf16 v[46:49], v[130:133], v[198:201], v[46:49]
	v_mfma_f32_16x16x32_bf16 v[42:45], v[162:165], v[198:201], v[42:45]
	v_mfma_f32_16x16x32_bf16 v[30:33], v[130:133], v[220:223], v[30:33]
	v_mfma_f32_16x16x32_bf16 v[26:29], v[162:165], v[220:223], v[26:29]
	v_mfma_f32_16x16x32_bf16 v[14:17], v[130:133], v[228:231], v[14:17]
	v_mfma_f32_16x16x32_bf16 v[10:13], v[162:165], v[228:231], v[10:13]
	v_mfma_f32_16x16x32_bf16 v[62:65], v[158:161], v[194:197], v[62:65]
	v_mfma_f32_16x16x32_bf16 v[58:61], v[170:173], v[194:197], v[58:61]
	v_mfma_f32_16x16x32_bf16 v[46:49], v[158:161], v[216:219], v[46:49]
	v_mfma_f32_16x16x32_bf16 v[42:45], v[170:173], v[216:219], v[42:45]
	v_mfma_f32_16x16x32_bf16 v[30:33], v[158:161], v[224:227], v[30:33]
	v_mfma_f32_16x16x32_bf16 v[26:29], v[170:173], v[224:227], v[26:29]
	v_mfma_f32_16x16x32_bf16 v[14:17], v[158:161], v[232:235], v[14:17]
	v_mfma_f32_16x16x32_bf16 v[10:13], v[170:173], v[232:235], v[10:13]
	v_mfma_f32_16x16x32_bf16 v[54:57], v[174:177], v[190:193], v[54:57]
	v_mfma_f32_16x16x32_bf16 v[50:53], v[182:185], v[190:193], v[50:53]
	v_mfma_f32_16x16x32_bf16 v[38:41], v[174:177], v[198:201], v[38:41]
	v_mfma_f32_16x16x32_bf16 v[34:37], v[182:185], v[198:201], v[34:37]
	v_mfma_f32_16x16x32_bf16 v[22:25], v[174:177], v[220:223], v[22:25]
	v_mfma_f32_16x16x32_bf16 v[18:21], v[182:185], v[220:223], v[18:21]
	v_mfma_f32_16x16x32_bf16 v[6:9], v[174:177], v[228:231], v[6:9]
	v_mfma_f32_16x16x32_bf16 v[2:5], v[182:185], v[228:231], v[2:5]
	v_mfma_f32_16x16x32_bf16 v[54:57], v[178:181], v[194:197], v[54:57]
	v_mfma_f32_16x16x32_bf16 v[50:53], v[186:189], v[194:197], v[50:53]
	v_mfma_f32_16x16x32_bf16 v[38:41], v[178:181], v[216:219], v[38:41]
	v_mfma_f32_16x16x32_bf16 v[34:37], v[186:189], v[216:219], v[34:37]
	v_mfma_f32_16x16x32_bf16 v[22:25], v[178:181], v[224:227], v[22:25]
	v_mfma_f32_16x16x32_bf16 v[18:21], v[186:189], v[224:227], v[18:21]
	v_mfma_f32_16x16x32_bf16 v[6:9], v[178:181], v[232:235], v[6:9]
	v_mfma_f32_16x16x32_bf16 v[2:5], v[186:189], v[232:235], v[2:5]
	s_setprio 0
	s_barrier
	s_add_i32 s60, 0, 0x18000
	v_add_u32_e32 v0, s60, v167
	s_add_i32 s61, 0, 0x1c000
	ds_read_b128 v[130:133], v0
	ds_read_b128 v[158:161], v0 offset:1024
	ds_read_b128 v[162:165], v0 offset:2048
	ds_read_b128 v[170:173], v0 offset:3072
	v_add_u32_e32 v0, s61, v167
	ds_read_b128 v[174:177], v0
	ds_read_b128 v[178:181], v0 offset:1024
	ds_read_b128 v[182:185], v0 offset:2048
	ds_read_b128 v[186:189], v0 offset:3072
	s_mov_b32 m0, s48
	s_nop 0
	global_load_lds_dwordx4 v140, s[14:15]
	s_mov_b32 m0, s49
	s_nop 0
	global_load_lds_dwordx4 v136, s[14:15]
	s_add_u32 s14, s14, 0x80000
	s_addc_u32 s15, s15, 0
	s_mov_b32 m0, s50
	ds_read_b128 v[190:193], v169 offset:32768
	ds_read_b128 v[194:197], v169 offset:33792
	ds_read_b128 v[198:201], v169 offset:34816
	ds_read_b128 v[216:219], v169 offset:35840
	ds_read_b128 v[220:223], v169 offset:36864
	ds_read_b128 v[224:227], v169 offset:37888
	ds_read_b128 v[228:231], v169 offset:38912
	ds_read_b128 v[232:235], v169 offset:39936
	global_load_lds_dwordx4 v140, s[14:15]
	s_mov_b32 m0, s51
	s_nop 0
	global_load_lds_dwordx4 v136, s[14:15]
	s_waitcnt vmcnt(8)
	s_waitcnt lgkmcnt(0)
	s_barrier
	s_setprio 1
	s_waitcnt lgkmcnt(0)
	v_mfma_f32_16x16x32_bf16 v[126:129], v[130:133], v[190:193], v[126:129]
	v_mfma_f32_16x16x32_bf16 v[122:125], v[162:165], v[190:193], v[122:125]
	v_mfma_f32_16x16x32_bf16 v[110:113], v[130:133], v[198:201], v[110:113]
	v_mfma_f32_16x16x32_bf16 v[106:109], v[162:165], v[198:201], v[106:109]
	v_mfma_f32_16x16x32_bf16 v[94:97], v[130:133], v[220:223], v[94:97]
	v_mfma_f32_16x16x32_bf16 v[90:93], v[162:165], v[220:223], v[90:93]
	v_mfma_f32_16x16x32_bf16 v[78:81], v[130:133], v[228:231], v[78:81]
	v_mfma_f32_16x16x32_bf16 v[74:77], v[162:165], v[228:231], v[74:77]
	v_mfma_f32_16x16x32_bf16 v[126:129], v[158:161], v[194:197], v[126:129]
	v_mfma_f32_16x16x32_bf16 v[122:125], v[170:173], v[194:197], v[122:125]
	v_mfma_f32_16x16x32_bf16 v[110:113], v[158:161], v[216:219], v[110:113]
	v_mfma_f32_16x16x32_bf16 v[106:109], v[170:173], v[216:219], v[106:109]
	v_mfma_f32_16x16x32_bf16 v[94:97], v[158:161], v[224:227], v[94:97]
	v_mfma_f32_16x16x32_bf16 v[90:93], v[170:173], v[224:227], v[90:93]
	v_mfma_f32_16x16x32_bf16 v[78:81], v[158:161], v[232:235], v[78:81]
	v_mfma_f32_16x16x32_bf16 v[74:77], v[170:173], v[232:235], v[74:77]
	v_mfma_f32_16x16x32_bf16 v[118:121], v[174:177], v[190:193], v[118:121]
	v_mfma_f32_16x16x32_bf16 v[114:117], v[182:185], v[190:193], v[114:117]
	v_mfma_f32_16x16x32_bf16 v[102:105], v[174:177], v[198:201], v[102:105]
	v_mfma_f32_16x16x32_bf16 v[98:101], v[182:185], v[198:201], v[98:101]
	v_mfma_f32_16x16x32_bf16 v[86:89], v[174:177], v[220:223], v[86:89]
	v_mfma_f32_16x16x32_bf16 v[82:85], v[182:185], v[220:223], v[82:85]
	v_mfma_f32_16x16x32_bf16 v[70:73], v[174:177], v[228:231], v[70:73]
	v_mfma_f32_16x16x32_bf16 v[66:69], v[182:185], v[228:231], v[66:69]
	v_mfma_f32_16x16x32_bf16 v[118:121], v[178:181], v[194:197], v[118:121]
	v_mfma_f32_16x16x32_bf16 v[114:117], v[186:189], v[194:197], v[114:117]
	v_mfma_f32_16x16x32_bf16 v[102:105], v[178:181], v[216:219], v[102:105]
	v_mfma_f32_16x16x32_bf16 v[98:101], v[186:189], v[216:219], v[98:101]
	v_mfma_f32_16x16x32_bf16 v[86:89], v[178:181], v[224:227], v[86:89]
	v_mfma_f32_16x16x32_bf16 v[82:85], v[186:189], v[224:227], v[82:85]
	v_mfma_f32_16x16x32_bf16 v[70:73], v[178:181], v[232:235], v[70:73]
	v_mfma_f32_16x16x32_bf16 v[66:69], v[186:189], v[232:235], v[66:69]
	s_setprio 0
	s_barrier
	s_add_i32 s14, s60, s29
	s_mov_b32 m0, s14
	ds_read_b128 v[190:193], v169 offset:49152
	ds_read_b128 v[194:197], v169 offset:50176
	ds_read_b128 v[198:201], v169 offset:51200
	ds_read_b128 v[216:219], v169 offset:52224
	ds_read_b128 v[220:223], v169 offset:53248
	ds_read_b128 v[224:227], v169 offset:54272
	ds_read_b128 v[228:231], v169 offset:55296
	ds_read_b128 v[232:235], v169 offset:56320
	global_load_lds_dwordx4 v138, s[72:73]
	s_add_i32 m0, s14, 0x2000
	s_add_u32 s10, s10, 0x80080
	s_addc_u32 s11, s11, 0
	s_add_i32 s14, s61, s29
	global_load_lds_dwordx4 v134, s[72:73]
	s_mov_b32 m0, s14
	s_nop 0
	global_load_lds_dwordx4 v138, s[10:11]
	s_add_i32 m0, s14, 0x2000
	s_nop 0
	global_load_lds_dwordx4 v134, s[10:11]
	s_waitcnt vmcnt(6)
	s_waitcnt lgkmcnt(0)
	s_barrier
	s_setprio 1
	s_waitcnt lgkmcnt(0)
	v_mfma_f32_16x16x32_bf16 v[62:65], v[130:133], v[190:193], v[62:65]
	s_add_i32 s59, s59, 2
	v_mfma_f32_16x16x32_bf16 v[58:61], v[162:165], v[190:193], v[58:61]
	s_add_u32 s57, s57, 0x100
	v_mfma_f32_16x16x32_bf16 v[46:49], v[130:133], v[198:201], v[46:49]
	s_addc_u32 s58, s58, 0
	v_mfma_f32_16x16x32_bf16 v[42:45], v[162:165], v[198:201], v[42:45]
	s_add_u32 s8, s8, 0x100
	v_mfma_f32_16x16x32_bf16 v[30:33], v[130:133], v[220:223], v[30:33]
	s_addc_u32 s9, s9, 0
	v_mfma_f32_16x16x32_bf16 v[26:29], v[162:165], v[220:223], v[26:29]
	s_add_u32 s10, s8, 0xfff80080
	v_mfma_f32_16x16x32_bf16 v[14:17], v[130:133], v[228:231], v[14:17]
	s_addc_u32 s11, s9, -1
	v_mfma_f32_16x16x32_bf16 v[10:13], v[162:165], v[228:231], v[10:13]
	s_add_i32 s60, 0, 0x10000
	v_mfma_f32_16x16x32_bf16 v[62:65], v[158:161], v[194:197], v[62:65]
	s_cmp_eq_u32 s59, 28
	v_mfma_f32_16x16x32_bf16 v[58:61], v[170:173], v[194:197], v[58:61]
	s_cselect_b32 s15, s0, s11
	v_mfma_f32_16x16x32_bf16 v[46:49], v[158:161], v[216:219], v[46:49]
	s_cselect_b32 s14, s1, s10
	v_mfma_f32_16x16x32_bf16 v[42:45], v[170:173], v[216:219], v[42:45]
	v_add_u32_e32 v0, s60, v167
	v_mfma_f32_16x16x32_bf16 v[30:33], v[158:161], v[224:227], v[30:33]
	s_cselect_b32 s11, s25, s58
	v_mfma_f32_16x16x32_bf16 v[26:29], v[170:173], v[224:227], v[26:29]
	s_cselect_b32 s10, s27, s57
	v_mfma_f32_16x16x32_bf16 v[14:17], v[158:161], v[232:235], v[14:17]
	s_add_i32 s62, 0, 0x14000
	v_mfma_f32_16x16x32_bf16 v[10:13], v[170:173], v[232:235], v[10:13]
	v_mfma_f32_16x16x32_bf16 v[54:57], v[174:177], v[190:193], v[54:57]
	v_mfma_f32_16x16x32_bf16 v[50:53], v[182:185], v[190:193], v[50:53]
	v_mfma_f32_16x16x32_bf16 v[38:41], v[174:177], v[198:201], v[38:41]
	v_mfma_f32_16x16x32_bf16 v[34:37], v[182:185], v[198:201], v[34:37]
	v_mfma_f32_16x16x32_bf16 v[22:25], v[174:177], v[220:223], v[22:25]
	v_mfma_f32_16x16x32_bf16 v[18:21], v[182:185], v[220:223], v[18:21]
	v_mfma_f32_16x16x32_bf16 v[6:9], v[174:177], v[228:231], v[6:9]
	v_mfma_f32_16x16x32_bf16 v[2:5], v[182:185], v[228:231], v[2:5]
	v_mfma_f32_16x16x32_bf16 v[54:57], v[178:181], v[194:197], v[54:57]
	v_mfma_f32_16x16x32_bf16 v[50:53], v[186:189], v[194:197], v[50:53]
	v_mfma_f32_16x16x32_bf16 v[38:41], v[178:181], v[216:219], v[38:41]
	v_mfma_f32_16x16x32_bf16 v[34:37], v[186:189], v[216:219], v[34:37]
	v_mfma_f32_16x16x32_bf16 v[22:25], v[178:181], v[224:227], v[22:25]
	v_mfma_f32_16x16x32_bf16 v[18:21], v[186:189], v[224:227], v[18:21]
	v_mfma_f32_16x16x32_bf16 v[6:9], v[178:181], v[232:235], v[6:9]
	v_mfma_f32_16x16x32_bf16 v[2:5], v[186:189], v[232:235], v[2:5]
	s_setprio 0
	s_barrier
	s_cmp_gt_u32 s59, 29
	s_cbranch_scc0 .LBB0_140
	s_and_b64 vcc, exec, s[20:21]
	s_cbranch_vccz .LBB0_143

.LBB0_772:
	s_add_u32 s60, s26, 0xfff80080
	s_addc_u32 s61, s27, -1
	s_add_i32 s62, 0, 0x10000
	s_cmp_eq_u32 s59, 28
	s_cselect_b32 s87, s0, s61
	s_cselect_b32 s86, s1, s60
	v_add_u32_e32 v140, s62, v143
	s_cselect_b32 s81, s13, s58
	s_cselect_b32 s80, s15, s57
	s_add_i32 s63, 0, 0x14000
	ds_read_b128 v[156:159], v140
	ds_read_b128 v[160:163], v140 offset:1024
	ds_read_b128 v[164:167], v140 offset:2048
	ds_read_b128 v[168:171], v140 offset:3072
	v_add_u32_e32 v140, s63, v143
	ds_read_b128 v[172:175], v140
	ds_read_b128 v[176:179], v140 offset:1024
	ds_read_b128 v[180:183], v140 offset:2048
	ds_read_b128 v[184:187], v140 offset:3072
	s_mov_b32 m0, s52
	s_nop 0
	global_load_lds_dwordx4 v134, s[100:101]
	s_mov_b32 m0, s53
	s_nop 0
	global_load_lds_dwordx4 v132, s[100:101]
	s_add_i32 m0, s48, 0xc000
	ds_read_b128 v[188:191], v145
	ds_read_b128 v[192:195], v145 offset:1024
	ds_read_b128 v[196:199], v145 offset:2048
	ds_read_b128 v[200:203], v145 offset:3072
	ds_read_b128 v[218:221], v145 offset:4096
	ds_read_b128 v[222:225], v145 offset:5120
	ds_read_b128 v[226:229], v145 offset:6144
	ds_read_b128 v[230:233], v145 offset:7168
	global_load_lds_dwordx4 v138, s[26:27]
	s_add_i32 m0, s48, 0xe000
	s_nop 0
	global_load_lds_dwordx4 v136, s[26:27]
	s_waitcnt vmcnt(8)
	s_waitcnt lgkmcnt(0)
	s_barrier
	s_setprio 1
	s_waitcnt lgkmcnt(0)
	v_mfma_f32_16x16x32_bf16 v[126:129], v[156:159], v[188:191], v[126:129]
	v_mfma_f32_16x16x32_bf16 v[122:125], v[164:167], v[188:191], v[122:125]
	v_mfma_f32_16x16x32_bf16 v[118:121], v[156:159], v[196:199], v[118:121]
	v_mfma_f32_16x16x32_bf16 v[110:113], v[164:167], v[196:199], v[110:113]
	v_mfma_f32_16x16x32_bf16 v[102:105], v[156:159], v[218:221], v[102:105]
	v_mfma_f32_16x16x32_bf16 v[94:97], v[164:167], v[218:221], v[94:97]
	v_mfma_f32_16x16x32_bf16 v[86:89], v[156:159], v[226:229], v[86:89]
	v_mfma_f32_16x16x32_bf16 v[78:81], v[164:167], v[226:229], v[78:81]
	v_mfma_f32_16x16x32_bf16 v[126:129], v[160:163], v[192:195], v[126:129]
	v_mfma_f32_16x16x32_bf16 v[122:125], v[168:171], v[192:195], v[122:125]
	v_mfma_f32_16x16x32_bf16 v[118:121], v[160:163], v[200:203], v[118:121]
	v_mfma_f32_16x16x32_bf16 v[110:113], v[168:171], v[200:203], v[110:113]
	v_mfma_f32_16x16x32_bf16 v[102:105], v[160:163], v[222:225], v[102:105]
	v_mfma_f32_16x16x32_bf16 v[94:97], v[168:171], v[222:225], v[94:97]
	v_mfma_f32_16x16x32_bf16 v[86:89], v[160:163], v[230:233], v[86:89]
	v_mfma_f32_16x16x32_bf16 v[78:81], v[168:171], v[230:233], v[78:81]
	v_mfma_f32_16x16x32_bf16 v[114:117], v[172:175], v[188:191], v[114:117]
	v_mfma_f32_16x16x32_bf16 v[106:109], v[180:183], v[188:191], v[106:109]
	v_mfma_f32_16x16x32_bf16 v[98:101], v[172:175], v[196:199], v[98:101]
	v_mfma_f32_16x16x32_bf16 v[90:93], v[180:183], v[196:199], v[90:93]
	v_mfma_f32_16x16x32_bf16 v[82:85], v[172:175], v[218:221], v[82:85]
	v_mfma_f32_16x16x32_bf16 v[74:77], v[180:183], v[218:221], v[74:77]
	v_mfma_f32_16x16x32_bf16 v[70:73], v[172:175], v[226:229], v[70:73]
	v_mfma_f32_16x16x32_bf16 v[66:69], v[180:183], v[226:229], v[66:69]
	v_mfma_f32_16x16x32_bf16 v[114:117], v[176:179], v[192:195], v[114:117]
	v_mfma_f32_16x16x32_bf16 v[106:109], v[184:187], v[192:195], v[106:109]
	v_mfma_f32_16x16x32_bf16 v[98:101], v[176:179], v[200:203], v[98:101]
	v_mfma_f32_16x16x32_bf16 v[90:93], v[184:187], v[200:203], v[90:93]
	v_mfma_f32_16x16x32_bf16 v[82:85], v[176:179], v[222:225], v[82:85]
	v_mfma_f32_16x16x32_bf16 v[74:77], v[184:187], v[222:225], v[74:77]
	v_mfma_f32_16x16x32_bf16 v[70:73], v[176:179], v[230:233], v[70:73]
	v_mfma_f32_16x16x32_bf16 v[66:69], v[184:187], v[230:233], v[66:69]
	s_setprio 0
	s_barrier
	s_add_i32 s60, s62, s29
	s_add_u32 s88, s80, s44
	s_addc_u32 s89, s81, s45
	s_mov_b32 m0, s60
	ds_read_b128 v[188:191], v145 offset:16384
	ds_read_b128 v[192:195], v145 offset:17408
	ds_read_b128 v[196:199], v145 offset:18432
	ds_read_b128 v[200:203], v145 offset:19456
	ds_read_b128 v[218:221], v145 offset:20480
	ds_read_b128 v[222:225], v145 offset:21504
	ds_read_b128 v[226:229], v145 offset:22528
	ds_read_b128 v[230:233], v145 offset:23552
	global_load_lds_dwordx4 v0, s[80:81]
	s_add_i32 m0, s60, 0x2000
	s_add_u32 s60, s80, 0x80000
	s_addc_u32 s61, s81, 0
	s_add_i32 s62, s63, s29
	global_load_lds_dwordx4 v130, s[80:81]
	s_mov_b32 m0, s62
	s_add_u32 s100, s86, s44
	s_addc_u32 s101, s87, s45
	global_load_lds_dwordx4 v0, s[60:61]
	s_add_i32 m0, s62, 0x2000
	s_nop 0
	global_load_lds_dwordx4 v130, s[60:61]
	s_waitcnt vmcnt(6)
	s_waitcnt lgkmcnt(0)
	s_barrier
	s_setprio 1
	s_waitcnt lgkmcnt(0)
	v_mfma_f32_16x16x32_bf16 v[62:65], v[156:159], v[188:191], v[62:65]
	v_mfma_f32_16x16x32_bf16 v[58:61], v[164:167], v[188:191], v[58:61]
	v_mfma_f32_16x16x32_bf16 v[54:57], v[156:159], v[196:199], v[54:57]
	v_mfma_f32_16x16x32_bf16 v[46:49], v[164:167], v[196:199], v[46:49]
	v_mfma_f32_16x16x32_bf16 v[38:41], v[156:159], v[218:221], v[38:41]
	v_mfma_f32_16x16x32_bf16 v[30:33], v[164:167], v[218:221], v[30:33]
	v_mfma_f32_16x16x32_bf16 v[22:25], v[156:159], v[226:229], v[22:25]
	v_mfma_f32_16x16x32_bf16 v[14:17], v[164:167], v[226:229], v[14:17]
	v_mfma_f32_16x16x32_bf16 v[62:65], v[160:163], v[192:195], v[62:65]
	v_mfma_f32_16x16x32_bf16 v[58:61], v[168:171], v[192:195], v[58:61]
	v_mfma_f32_16x16x32_bf16 v[54:57], v[160:163], v[200:203], v[54:57]
	v_mfma_f32_16x16x32_bf16 v[46:49], v[168:171], v[200:203], v[46:49]
	v_mfma_f32_16x16x32_bf16 v[38:41], v[160:163], v[222:225], v[38:41]
	v_mfma_f32_16x16x32_bf16 v[30:33], v[168:171], v[222:225], v[30:33]
	v_mfma_f32_16x16x32_bf16 v[22:25], v[160:163], v[230:233], v[22:25]
	v_mfma_f32_16x16x32_bf16 v[14:17], v[168:171], v[230:233], v[14:17]
	v_mfma_f32_16x16x32_bf16 v[50:53], v[172:175], v[188:191], v[50:53]
	v_mfma_f32_16x16x32_bf16 v[42:45], v[180:183], v[188:191], v[42:45]
	v_mfma_f32_16x16x32_bf16 v[34:37], v[172:175], v[196:199], v[34:37]
	v_mfma_f32_16x16x32_bf16 v[26:29], v[180:183], v[196:199], v[26:29]
	v_mfma_f32_16x16x32_bf16 v[18:21], v[172:175], v[218:221], v[18:21]
	v_mfma_f32_16x16x32_bf16 v[10:13], v[180:183], v[218:221], v[10:13]
	v_mfma_f32_16x16x32_bf16 v[6:9], v[172:175], v[226:229], v[6:9]
	v_mfma_f32_16x16x32_bf16 v[2:5], v[180:183], v[226:229], v[2:5]
	v_mfma_f32_16x16x32_bf16 v[50:53], v[176:179], v[192:195], v[50:53]
	v_mfma_f32_16x16x32_bf16 v[42:45], v[184:187], v[192:195], v[42:45]
	v_mfma_f32_16x16x32_bf16 v[34:37], v[176:179], v[200:203], v[34:37]
	v_mfma_f32_16x16x32_bf16 v[26:29], v[184:187], v[200:203], v[26:29]
	v_mfma_f32_16x16x32_bf16 v[18:21], v[176:179], v[222:225], v[18:21]
	v_mfma_f32_16x16x32_bf16 v[10:13], v[184:187], v[222:225], v[10:13]
	v_mfma_f32_16x16x32_bf16 v[6:9], v[176:179], v[230:233], v[6:9]
	v_mfma_f32_16x16x32_bf16 v[2:5], v[184:187], v[230:233], v[2:5]
	s_setprio 0
	s_barrier
	s_add_i32 s62, 0, 0x18000
	s_add_i32 s63, 0, 0x1c000
	v_add_u32_e32 v168, s62, v143
	v_add_u32_e32 v184, s63, v143
	ds_read_b128 v[156:159], v168
	ds_read_b128 v[160:163], v168 offset:1024
	ds_read_b128 v[164:167], v168 offset:2048
	ds_read_b128 v[168:171], v168 offset:3072
	ds_read_b128 v[172:175], v184
	ds_read_b128 v[176:179], v184 offset:1024
	ds_read_b128 v[180:183], v184 offset:2048
	ds_read_b128 v[184:187], v184 offset:3072
	s_mov_b32 m0, s48
	s_nop 0
	global_load_lds_dwordx4 v134, s[86:87]
	s_mov_b32 m0, s49
	s_nop 0
	global_load_lds_dwordx4 v132, s[86:87]
	s_add_u32 s60, s86, 0x80000
	s_addc_u32 s61, s87, 0
	s_mov_b32 m0, s50
	ds_read_b128 v[188:191], v145 offset:32768
	ds_read_b128 v[192:195], v145 offset:33792
	ds_read_b128 v[196:199], v145 offset:34816
	ds_read_b128 v[200:203], v145 offset:35840
	ds_read_b128 v[218:221], v145 offset:36864
	ds_read_b128 v[222:225], v145 offset:37888
	ds_read_b128 v[226:229], v145 offset:38912
	ds_read_b128 v[230:233], v145 offset:39936
	global_load_lds_dwordx4 v134, s[60:61]
	s_mov_b32 m0, s51
	s_nop 0
	global_load_lds_dwordx4 v132, s[60:61]
	s_waitcnt vmcnt(8)
	s_waitcnt lgkmcnt(0)
	s_barrier
	s_setprio 1
	s_waitcnt lgkmcnt(0)
	v_mfma_f32_16x16x32_bf16 v[126:129], v[156:159], v[188:191], v[126:129]
	v_mfma_f32_16x16x32_bf16 v[122:125], v[164:167], v[188:191], v[122:125]
	v_mfma_f32_16x16x32_bf16 v[118:121], v[156:159], v[196:199], v[118:121]
	v_mfma_f32_16x16x32_bf16 v[110:113], v[164:167], v[196:199], v[110:113]
	v_mfma_f32_16x16x32_bf16 v[102:105], v[156:159], v[218:221], v[102:105]
	v_mfma_f32_16x16x32_bf16 v[94:97], v[164:167], v[218:221], v[94:97]
	v_mfma_f32_16x16x32_bf16 v[86:89], v[156:159], v[226:229], v[86:89]
	v_mfma_f32_16x16x32_bf16 v[78:81], v[164:167], v[226:229], v[78:81]
	v_mfma_f32_16x16x32_bf16 v[126:129], v[160:163], v[192:195], v[126:129]
	v_mfma_f32_16x16x32_bf16 v[122:125], v[168:171], v[192:195], v[122:125]
	v_mfma_f32_16x16x32_bf16 v[118:121], v[160:163], v[200:203], v[118:121]
	v_mfma_f32_16x16x32_bf16 v[110:113], v[168:171], v[200:203], v[110:113]
	v_mfma_f32_16x16x32_bf16 v[102:105], v[160:163], v[222:225], v[102:105]
	v_mfma_f32_16x16x32_bf16 v[94:97], v[168:171], v[222:225], v[94:97]
	v_mfma_f32_16x16x32_bf16 v[86:89], v[160:163], v[230:233], v[86:89]
	v_mfma_f32_16x16x32_bf16 v[78:81], v[168:171], v[230:233], v[78:81]
	v_mfma_f32_16x16x32_bf16 v[114:117], v[172:175], v[188:191], v[114:117]
	v_mfma_f32_16x16x32_bf16 v[106:109], v[180:183], v[188:191], v[106:109]
	v_mfma_f32_16x16x32_bf16 v[98:101], v[172:175], v[196:199], v[98:101]
	v_mfma_f32_16x16x32_bf16 v[90:93], v[180:183], v[196:199], v[90:93]
	v_mfma_f32_16x16x32_bf16 v[82:85], v[172:175], v[218:221], v[82:85]
	v_mfma_f32_16x16x32_bf16 v[74:77], v[180:183], v[218:221], v[74:77]
	v_mfma_f32_16x16x32_bf16 v[70:73], v[172:175], v[226:229], v[70:73]
	v_mfma_f32_16x16x32_bf16 v[66:69], v[180:183], v[226:229], v[66:69]
	v_mfma_f32_16x16x32_bf16 v[114:117], v[176:179], v[192:195], v[114:117]
	v_mfma_f32_16x16x32_bf16 v[106:109], v[184:187], v[192:195], v[106:109]
	v_mfma_f32_16x16x32_bf16 v[98:101], v[176:179], v[200:203], v[98:101]
	v_mfma_f32_16x16x32_bf16 v[90:93], v[184:187], v[200:203], v[90:93]
	v_mfma_f32_16x16x32_bf16 v[82:85], v[176:179], v[222:225], v[82:85]
	v_mfma_f32_16x16x32_bf16 v[74:77], v[184:187], v[222:225], v[74:77]
	v_mfma_f32_16x16x32_bf16 v[70:73], v[176:179], v[230:233], v[70:73]
	v_mfma_f32_16x16x32_bf16 v[66:69], v[184:187], v[230:233], v[66:69]
	s_setprio 0
	s_barrier
	s_add_i32 s60, s62, s29
	s_mov_b32 m0, s60
	ds_read_b128 v[188:191], v145 offset:49152
	ds_read_b128 v[192:195], v145 offset:50176
	ds_read_b128 v[196:199], v145 offset:51200
	ds_read_b128 v[200:203], v145 offset:52224
	ds_read_b128 v[218:221], v145 offset:53248
	ds_read_b128 v[222:225], v145 offset:54272
	ds_read_b128 v[226:229], v145 offset:55296
	ds_read_b128 v[230:233], v145 offset:56320
	global_load_lds_dwordx4 v0, s[88:89]
	s_add_i32 m0, s60, 0x2000
	s_add_u32 s60, s80, 0x80080
	s_addc_u32 s61, s81, 0
	s_add_i32 s62, s63, s29
	global_load_lds_dwordx4 v130, s[88:89]
	s_mov_b32 m0, s62
	s_nop 0
	global_load_lds_dwordx4 v0, s[60:61]
	s_add_i32 m0, s62, 0x2000
	s_nop 0
	global_load_lds_dwordx4 v130, s[60:61]
	s_waitcnt vmcnt(6)
	s_waitcnt lgkmcnt(0)
	s_barrier
	s_setprio 1
	s_waitcnt lgkmcnt(0)
	v_mfma_f32_16x16x32_bf16 v[62:65], v[156:159], v[188:191], v[62:65]
	v_mfma_f32_16x16x32_bf16 v[58:61], v[164:167], v[188:191], v[58:61]
	v_mfma_f32_16x16x32_bf16 v[54:57], v[156:159], v[196:199], v[54:57]
	v_mfma_f32_16x16x32_bf16 v[46:49], v[164:167], v[196:199], v[46:49]
	v_mfma_f32_16x16x32_bf16 v[38:41], v[156:159], v[218:221], v[38:41]
	v_mfma_f32_16x16x32_bf16 v[30:33], v[164:167], v[218:221], v[30:33]
	v_mfma_f32_16x16x32_bf16 v[22:25], v[156:159], v[226:229], v[22:25]
	v_mfma_f32_16x16x32_bf16 v[14:17], v[164:167], v[226:229], v[14:17]
	v_mfma_f32_16x16x32_bf16 v[62:65], v[160:163], v[192:195], v[62:65]
	v_mfma_f32_16x16x32_bf16 v[58:61], v[168:171], v[192:195], v[58:61]
	v_mfma_f32_16x16x32_bf16 v[54:57], v[160:163], v[200:203], v[54:57]
	v_mfma_f32_16x16x32_bf16 v[46:49], v[168:171], v[200:203], v[46:49]
	v_mfma_f32_16x16x32_bf16 v[38:41], v[160:163], v[222:225], v[38:41]
	v_mfma_f32_16x16x32_bf16 v[30:33], v[168:171], v[222:225], v[30:33]
	v_mfma_f32_16x16x32_bf16 v[22:25], v[160:163], v[230:233], v[22:25]
	v_mfma_f32_16x16x32_bf16 v[14:17], v[168:171], v[230:233], v[14:17]
	v_mfma_f32_16x16x32_bf16 v[50:53], v[172:175], v[188:191], v[50:53]
	v_mfma_f32_16x16x32_bf16 v[42:45], v[180:183], v[188:191], v[42:45]
	v_mfma_f32_16x16x32_bf16 v[34:37], v[172:175], v[196:199], v[34:37]
	v_mfma_f32_16x16x32_bf16 v[26:29], v[180:183], v[196:199], v[26:29]
	v_mfma_f32_16x16x32_bf16 v[18:21], v[172:175], v[218:221], v[18:21]
	v_mfma_f32_16x16x32_bf16 v[10:13], v[180:183], v[218:221], v[10:13]
	v_mfma_f32_16x16x32_bf16 v[6:9], v[172:175], v[226:229], v[6:9]
	v_mfma_f32_16x16x32_bf16 v[2:5], v[180:183], v[226:229], v[2:5]
	v_mfma_f32_16x16x32_bf16 v[50:53], v[176:179], v[192:195], v[50:53]
	v_mfma_f32_16x16x32_bf16 v[42:45], v[184:187], v[192:195], v[42:45]
	v_mfma_f32_16x16x32_bf16 v[34:37], v[176:179], v[200:203], v[34:37]
	v_mfma_f32_16x16x32_bf16 v[26:29], v[184:187], v[200:203], v[26:29]
	v_mfma_f32_16x16x32_bf16 v[18:21], v[176:179], v[222:225], v[18:21]
	v_mfma_f32_16x16x32_bf16 v[10:13], v[184:187], v[222:225], v[10:13]
	v_mfma_f32_16x16x32_bf16 v[6:9], v[176:179], v[230:233], v[6:9]
	v_mfma_f32_16x16x32_bf16 v[2:5], v[184:187], v[230:233], v[2:5]
	s_setprio 0
	s_barrier
	s_add_i32 s59, s59, 2
	s_add_u32 s57, s57, 0x100
	s_addc_u32 s58, s58, 0
	s_add_u32 s26, s26, 0x100
	s_addc_u32 s27, s27, 0
	s_cmp_gt_u32 s59, 29
	s_cbranch_scc0 .LBB0_772
	s_and_b64 vcc, exec, s[10:11]
	v_readlane_b32 s58, v254, 35
	v_readlane_b32 s59, v254, 36
	s_cbranch_vccz .LBB0_775
